# GEMM epilogues: dead denormal-range rescue around v_rsq removed (argument is sum/1024+1e-6, never below FLT_MIN) at 17 row-group sites
# baseline (speedup 1.0000x reference)
.LBB0_136:
	s_waitcnt vmcnt(0)
	v_fmamk_f32 v152, v152, 0x3a800000, v233
	s_cmp_eq_u32 s21, 1
	s_cselect_b64 s[8:9], -1, 0
	v_rsq_f32_e32 v152, v152
	s_mov_b64 s[28:29], -1
	v_mov_b32_e32 v154, v152
	v_pk_mul_f32 v[128:129], v[128:129], v[154:155] op_sel_hi:[1,0]
	v_pk_mul_f32 v[156:157], v[126:127], v[154:155] op_sel_hi:[1,0]
	v_pk_mul_f32 v[124:125], v[124:125], v[154:155] op_sel_hi:[1,0]
	v_pk_mul_f32 v[126:127], v[122:123], v[154:155] op_sel_hi:[1,0]
	s_and_b64 vcc, exec, s[10:11]
	s_cbranch_vccz .LBB0_145
	s_cmp_lt_i32 s21, 4
	s_cbranch_scc1 .LBB0_141
	s_cmp_eq_u32 s21, 4
	v_mov_b32_e32 v165, v125
	v_mov_b32_e32 v164, v124
	v_mov_b32_e32 v163, v127
	v_mov_b32_e32 v162, v126
	v_mov_b32_e32 v161, v129
	v_mov_b32_e32 v160, v128
	v_mov_b32_e32 v159, v157
	v_mov_b32_e32 v158, v156
	s_cbranch_scc0 .LBB0_140
	v_pk_mul_f32 v[160:161], v[128:129], s[92:93] op_sel_hi:[1,0]
	v_pk_mul_f32 v[158:159], v[156:157], s[92:93] op_sel_hi:[1,0]
	v_pk_mul_f32 v[164:165], v[124:125], s[92:93] op_sel_hi:[1,0]
	v_pk_mul_f32 v[162:163], v[126:127], s[92:93] op_sel_hi:[1,0]

.LBB0_162:
	v_fmamk_f32 v118, v177, 0x3a800000, v233
	s_mov_b64 s[10:11], -1
	s_nop 0
	v_rsq_f32_e32 v118, v118
	s_nop 0
	v_pk_mul_f32 v[112:113], v[112:113], v[118:119] op_sel_hi:[1,0]
	v_pk_mul_f32 v[110:111], v[110:111], v[118:119] op_sel_hi:[1,0]
	v_pk_mul_f32 v[108:109], v[108:109], v[118:119] op_sel_hi:[1,0]
	v_pk_mul_f32 v[106:107], v[106:107], v[118:119] op_sel_hi:[1,0]
	s_and_b64 vcc, exec, s[8:9]
	s_cbranch_vccnz .LBB0_171
	s_cmp_lt_i32 s21, 4
	s_cbranch_scc1 .LBB0_167
	s_cmp_eq_u32 s21, 4
	v_mov_b32_e32 v127, v109
	v_mov_b32_e32 v126, v108
	v_mov_b32_e32 v129, v107
	v_mov_b32_e32 v128, v106
	v_mov_b32_e32 v121, v113
	v_mov_b32_e32 v120, v112
	v_mov_b32_e32 v125, v111
	v_mov_b32_e32 v124, v110
	s_cbranch_scc0 .LBB0_166
	v_pk_mul_f32 v[120:121], v[112:113], s[92:93] op_sel_hi:[1,0]
	v_pk_mul_f32 v[124:125], v[110:111], s[92:93] op_sel_hi:[1,0]
	v_pk_mul_f32 v[126:127], v[108:109], s[92:93] op_sel_hi:[1,0]
	v_pk_mul_f32 v[128:129], v[106:107], s[92:93] op_sel_hi:[1,0]

.LBB0_186:
	v_fmamk_f32 v98, v176, 0x3a800000, v233
	s_mov_b64 s[30:31], -1
	s_nop 0
	v_rsq_f32_e32 v98, v98
	s_nop 0
	v_pk_mul_f32 v[96:97], v[96:97], v[98:99] op_sel_hi:[1,0]
	v_pk_mul_f32 v[94:95], v[94:95], v[98:99] op_sel_hi:[1,0]
	v_pk_mul_f32 v[92:93], v[92:93], v[98:99] op_sel_hi:[1,0]
	v_pk_mul_f32 v[90:91], v[90:91], v[98:99] op_sel_hi:[1,0]
	s_and_b64 vcc, exec, s[8:9]
	s_cbranch_vccnz .LBB0_195
	s_cmp_lt_i32 s21, 4
	s_cbranch_scc1 .LBB0_191
	s_cmp_eq_u32 s21, 4
	v_mov_b32_e32 v105, v93
	v_mov_b32_e32 v104, v92
	v_mov_b32_e32 v107, v91
	v_mov_b32_e32 v106, v90
	v_mov_b32_e32 v101, v97
	v_mov_b32_e32 v100, v96
	v_mov_b32_e32 v103, v95
	v_mov_b32_e32 v102, v94
	s_cbranch_scc0 .LBB0_190
	v_pk_mul_f32 v[100:101], v[96:97], s[92:93] op_sel_hi:[1,0]
	v_pk_mul_f32 v[102:103], v[94:95], s[92:93] op_sel_hi:[1,0]
	v_pk_mul_f32 v[104:105], v[92:93], s[92:93] op_sel_hi:[1,0]
	v_pk_mul_f32 v[106:107], v[90:91], s[92:93] op_sel_hi:[1,0]

.LBB0_210:
	v_fmamk_f32 v82, v175, 0x3a800000, v233
	s_mov_b64 s[30:31], -1
	s_nop 0
	v_rsq_f32_e32 v82, v82
	s_nop 0
	v_pk_mul_f32 v[80:81], v[80:81], v[82:83] op_sel_hi:[1,0]
	v_pk_mul_f32 v[78:79], v[78:79], v[82:83] op_sel_hi:[1,0]
	v_pk_mul_f32 v[76:77], v[76:77], v[82:83] op_sel_hi:[1,0]
	v_pk_mul_f32 v[74:75], v[74:75], v[82:83] op_sel_hi:[1,0]
	s_and_b64 vcc, exec, s[8:9]
	s_cbranch_vccnz .LBB0_219
	s_cmp_lt_i32 s21, 4
	s_cbranch_scc1 .LBB0_215
	s_cmp_eq_u32 s21, 4
	v_mov_b32_e32 v89, v77
	v_mov_b32_e32 v88, v76
	v_mov_b32_e32 v91, v75
	v_mov_b32_e32 v90, v74
	v_mov_b32_e32 v85, v81
	v_mov_b32_e32 v84, v80
	v_mov_b32_e32 v87, v79
	v_mov_b32_e32 v86, v78
	s_cbranch_scc0 .LBB0_214
	v_pk_mul_f32 v[84:85], v[80:81], s[92:93] op_sel_hi:[1,0]
	v_pk_mul_f32 v[86:87], v[78:79], s[92:93] op_sel_hi:[1,0]
	v_pk_mul_f32 v[88:89], v[76:77], s[92:93] op_sel_hi:[1,0]
	v_pk_mul_f32 v[90:91], v[74:75], s[92:93] op_sel_hi:[1,0]

.LBB0_234:
	v_fmamk_f32 v66, v174, 0x3a800000, v233
	s_mov_b64 s[30:31], -1
	s_nop 0
	v_rsq_f32_e32 v66, v66
	s_nop 0
	v_pk_mul_f32 v[64:65], v[64:65], v[66:67] op_sel_hi:[1,0]
	v_pk_mul_f32 v[62:63], v[62:63], v[66:67] op_sel_hi:[1,0]
	v_pk_mul_f32 v[60:61], v[60:61], v[66:67] op_sel_hi:[1,0]
	v_pk_mul_f32 v[58:59], v[58:59], v[66:67] op_sel_hi:[1,0]
	s_and_b64 vcc, exec, s[8:9]
	s_cbranch_vccnz .LBB0_243
	s_cmp_lt_i32 s21, 4
	s_cbranch_scc1 .LBB0_239
	s_cmp_eq_u32 s21, 4
	v_mov_b32_e32 v73, v61
	v_mov_b32_e32 v72, v60
	v_mov_b32_e32 v75, v59
	v_mov_b32_e32 v74, v58
	v_mov_b32_e32 v69, v65
	v_mov_b32_e32 v68, v64
	v_mov_b32_e32 v71, v63
	v_mov_b32_e32 v70, v62
	s_cbranch_scc0 .LBB0_238
	v_pk_mul_f32 v[68:69], v[64:65], s[92:93] op_sel_hi:[1,0]
	v_pk_mul_f32 v[70:71], v[62:63], s[92:93] op_sel_hi:[1,0]
	v_pk_mul_f32 v[72:73], v[60:61], s[92:93] op_sel_hi:[1,0]
	v_pk_mul_f32 v[74:75], v[58:59], s[92:93] op_sel_hi:[1,0]

.LBB0_258:
	v_fmamk_f32 v50, v173, 0x3a800000, v233
	s_mov_b64 s[30:31], -1
	s_nop 0
	v_rsq_f32_e32 v50, v50
	s_nop 0
	v_pk_mul_f32 v[48:49], v[48:49], v[50:51] op_sel_hi:[1,0]
	v_pk_mul_f32 v[46:47], v[46:47], v[50:51] op_sel_hi:[1,0]
	v_pk_mul_f32 v[44:45], v[44:45], v[50:51] op_sel_hi:[1,0]
	v_pk_mul_f32 v[42:43], v[42:43], v[50:51] op_sel_hi:[1,0]
	s_and_b64 vcc, exec, s[8:9]
	s_cbranch_vccnz .LBB0_267
	s_cmp_lt_i32 s21, 4
	s_cbranch_scc1 .LBB0_263
	s_cmp_eq_u32 s21, 4
	v_mov_b32_e32 v57, v45
	v_mov_b32_e32 v56, v44
	v_mov_b32_e32 v59, v43
	v_mov_b32_e32 v58, v42
	v_mov_b32_e32 v53, v49
	v_mov_b32_e32 v52, v48
	v_mov_b32_e32 v55, v47
	v_mov_b32_e32 v54, v46
	s_cbranch_scc0 .LBB0_262
	v_pk_mul_f32 v[52:53], v[48:49], s[92:93] op_sel_hi:[1,0]
	v_pk_mul_f32 v[54:55], v[46:47], s[92:93] op_sel_hi:[1,0]
	v_pk_mul_f32 v[56:57], v[44:45], s[92:93] op_sel_hi:[1,0]
	v_pk_mul_f32 v[58:59], v[42:43], s[92:93] op_sel_hi:[1,0]

.LBB0_282:
	v_fmamk_f32 v34, v172, 0x3a800000, v233
	s_mov_b64 s[30:31], -1
	s_nop 0
	v_rsq_f32_e32 v34, v34
	s_nop 0
	v_pk_mul_f32 v[32:33], v[32:33], v[34:35] op_sel_hi:[1,0]
	v_pk_mul_f32 v[30:31], v[30:31], v[34:35] op_sel_hi:[1,0]
	v_pk_mul_f32 v[28:29], v[28:29], v[34:35] op_sel_hi:[1,0]
	v_pk_mul_f32 v[26:27], v[26:27], v[34:35] op_sel_hi:[1,0]
	s_and_b64 vcc, exec, s[8:9]
	s_cbranch_vccnz .LBB0_291
	s_cmp_lt_i32 s21, 4
	s_cbranch_scc1 .LBB0_287
	s_cmp_eq_u32 s21, 4
	v_mov_b32_e32 v41, v29
	v_mov_b32_e32 v40, v28
	v_mov_b32_e32 v43, v27
	v_mov_b32_e32 v42, v26
	v_mov_b32_e32 v37, v33
	v_mov_b32_e32 v36, v32
	v_mov_b32_e32 v39, v31
	v_mov_b32_e32 v38, v30
	s_cbranch_scc0 .LBB0_286
	v_pk_mul_f32 v[36:37], v[32:33], s[92:93] op_sel_hi:[1,0]
	v_pk_mul_f32 v[38:39], v[30:31], s[92:93] op_sel_hi:[1,0]
	v_pk_mul_f32 v[40:41], v[28:29], s[92:93] op_sel_hi:[1,0]
	v_pk_mul_f32 v[42:43], v[26:27], s[92:93] op_sel_hi:[1,0]

.LBB0_306:
	v_fmamk_f32 v18, v151, 0x3a800000, v233
	s_mov_b64 s[10:11], -1
	s_nop 0
	v_rsq_f32_e32 v18, v18
	s_nop 0
	v_pk_mul_f32 v[16:17], v[16:17], v[18:19] op_sel_hi:[1,0]
	v_pk_mul_f32 v[14:15], v[14:15], v[18:19] op_sel_hi:[1,0]
	v_pk_mul_f32 v[12:13], v[12:13], v[18:19] op_sel_hi:[1,0]
	v_pk_mul_f32 v[10:11], v[10:11], v[18:19] op_sel_hi:[1,0]
	s_and_b64 vcc, exec, s[8:9]
	s_cbranch_vccnz .LBB0_315
	s_cmp_lt_i32 s21, 4
	s_cbranch_scc1 .LBB0_311
	s_cmp_eq_u32 s21, 4
	v_mov_b32_e32 v25, v13
	v_mov_b32_e32 v24, v12
	v_mov_b32_e32 v27, v11
	v_mov_b32_e32 v26, v10
	v_mov_b32_e32 v21, v17
	v_mov_b32_e32 v20, v16
	v_mov_b32_e32 v23, v15
	v_mov_b32_e32 v22, v14
	s_cbranch_scc0 .LBB0_310
	v_pk_mul_f32 v[20:21], v[16:17], s[92:93] op_sel_hi:[1,0]
	v_pk_mul_f32 v[22:23], v[14:15], s[92:93] op_sel_hi:[1,0]
	v_pk_mul_f32 v[24:25], v[12:13], s[92:93] op_sel_hi:[1,0]
	v_pk_mul_f32 v[26:27], v[10:11], s[92:93] op_sel_hi:[1,0]

.LBB0_348:
	v_lshl_add_u32 v144, s70, 8, v139
	v_ashrrev_i32_e32 v145, 31, v144
	v_lshl_add_u64 v[162:163], v[144:145], 2, s[12:13]
	global_load_dword v0, v[162:163], off
	v_or_b32_e32 v150, 16, v144
	v_ashrrev_i32_e32 v151, 31, v150
	v_or_b32_e32 v148, 32, v144
	v_lshl_add_u64 v[146:147], v[150:151], 2, s[12:13]
	v_ashrrev_i32_e32 v149, 31, v148
	global_load_dword v160, v[146:147], off
	v_lshl_add_u64 v[146:147], v[148:149], 2, s[12:13]
	global_load_dword v159, v[146:147], off
	v_or_b32_e32 v146, 48, v144
	v_ashrrev_i32_e32 v147, 31, v146
	v_lshl_add_u64 v[154:155], v[146:147], 2, s[12:13]
	global_load_dword v158, v[154:155], off
	global_load_dword v157, v[162:163], off offset:512
	global_load_dword v156, v[162:163], off offset:576
	s_nop 0
	global_load_dword v155, v[162:163], off offset:640
	global_load_dword v154, v[162:163], off offset:704
	s_lshl_b32 s34, s69, 8
	v_lshlrev_b64 v[164:165], 12, v[144:145]
	s_ashr_i32 s35, s34, 31
	v_lshl_add_u64 v[164:165], s[10:11], 0, v[164:165]
	v_lshl_add_u64 v[164:165], s[34:35], 1, v[164:165]
	s_cmp_lt_i32 s69, 4
	s_cselect_b64 s[28:29], -1, 0
	s_and_b64 s[30:31], s[6:7], s[28:29]
	s_lshl_b32 s28, s69, 2
	s_ashr_i32 s29, s28, 31
	s_waitcnt vmcnt(0)
	v_fmamk_f32 v0, v0, 0x3a800000, v233
	s_nop 0
	v_rsq_f32_e32 v0, v0
	s_nop 0
	v_mov_b32_e32 v162, v0
	v_pk_mul_f32 v[128:129], v[128:129], v[162:163] op_sel_hi:[1,0]
	v_pk_mul_f32 v[126:127], v[126:127], v[162:163] op_sel_hi:[1,0]
	v_pk_mul_f32 v[166:167], v[124:125], v[162:163] op_sel_hi:[1,0]
	v_pk_mul_f32 v[124:125], v[122:123], v[162:163] op_sel_hi:[1,0]
	v_mul_f32_e32 v122, v127, v127
	v_mul_f32_e32 v123, v129, v129
	v_fmac_f32_e32 v122, v126, v126
	v_fmac_f32_e32 v123, v128, v128
	v_add_f32_e32 v122, v122, v123
	v_mul_f32_e32 v123, v125, v125
	v_fmac_f32_e32 v123, v124, v124
	v_add_f32_e32 v122, v123, v122
	v_mul_f32_e32 v123, v167, v167
	v_fmac_f32_e32 v123, v166, v166
	v_lshlrev_b32_e32 v0, 1, v138
	v_add_f32_e32 v161, v123, v122
	v_cvt_pk_bf16_f32 v122, v126, v127
	v_cvt_pk_bf16_f32 v123, v128, v129
	v_pk_mul_f32 v[120:121], v[120:121], v[162:163] op_sel_hi:[1,0]
	v_pk_mul_f32 v[118:119], v[118:119], v[162:163] op_sel_hi:[1,0]
	v_lshl_add_u64 v[164:165], v[164:165], 0, v[0:1]
	v_cvt_pk_bf16_f32 v124, v124, v125
	v_cvt_pk_bf16_f32 v125, v166, v167
	global_store_dwordx4 v[164:165], v[122:125], off offset:0 sc1
	s_nop 1
	v_pk_mul_f32 v[122:123], v[116:117], v[162:163] op_sel_hi:[1,0]
	v_pk_mul_f32 v[116:117], v[114:115], v[162:163] op_sel_hi:[1,0]
	v_mul_f32_e32 v114, v119, v119
	v_mul_f32_e32 v115, v121, v121
	v_fmac_f32_e32 v114, v118, v118
	v_fmac_f32_e32 v115, v120, v120
	v_add_f32_e32 v114, v114, v115
	v_mul_f32_e32 v115, v117, v117
	v_fmac_f32_e32 v115, v116, v116
	v_add_f32_e32 v114, v115, v114
	v_mul_f32_e32 v115, v123, v123
	v_fmac_f32_e32 v115, v122, v122
	v_add_f32_e32 v114, v115, v114
	v_cvt_pk_bf16_f32 v115, v120, v121
	v_add_f32_e32 v124, v161, v114
	v_cvt_pk_bf16_f32 v114, v118, v119
	v_cvt_pk_bf16_f32 v116, v116, v117
	v_cvt_pk_bf16_f32 v117, v122, v123
	global_store_dwordx4 v[164:165], v[114:117], off offset:0x100 sc1
	s_nop 1
	v_and_b32_e32 v115, 64, v238
	v_xor_b32_e32 v114, 16, v238
	v_add_u32_e32 v115, 64, v115
	v_cmp_lt_i32_e32 vcc, v114, v115
	v_xor_b32_e32 v117, 32, v238
	s_nop 0
	v_cndmask_b32_e32 v114, v238, v114, vcc
	v_lshlrev_b32_e32 v114, 2, v114
	ds_bpermute_b32 v116, v114, v124
	v_cmp_lt_i32_e32 vcc, v117, v115
	s_waitcnt lgkmcnt(0)
	v_add_f32_e32 v116, v124, v116
	v_cndmask_b32_e32 v115, v238, v117, vcc
	v_lshlrev_b32_e32 v115, 2, v115
	ds_bpermute_b32 v117, v115, v116
	s_and_saveexec_b64 s[36:37], s[30:31]
	s_cbranch_execz .LBB0_350
	v_lshlrev_b64 v[118:119], 6, v[144:145]
	v_lshl_add_u64 v[118:119], s[14:15], 0, v[118:119]
	v_lshl_add_u64 v[118:119], s[28:29], 2, v[118:119]
	s_lshl_b32 s76, s57, 2
	v_lshl_add_u64 v[118:119], v[118:119], 0, s[76:77]
	s_waitcnt lgkmcnt(0)
	v_add_f32_e32 v116, v116, v117
	global_store_dword v[118:119], v116, off

.LBB0_678:
	v_lshl_add_u32 v144, s72, 8, v139
	v_ashrrev_i32_e32 v145, 31, v144
	v_lshl_add_u64 v[156:157], v[144:145], 2, s[16:17]
	global_load_dword v0, v[156:157], off
	global_load_dword v154, v[156:157], off offset:64
	global_load_dword v153, v[156:157], off offset:128
	global_load_dword v152, v[156:157], off offset:192
	global_load_dword v151, v[156:157], off offset:512
	global_load_dword v150, v[156:157], off offset:576
	global_load_dword v147, v[156:157], off offset:640
	global_load_dword v146, v[156:157], off offset:704
	s_lshl_b32 s34, s71, 8
	v_lshlrev_b64 v[158:159], 11, v[144:145]
	s_ashr_i32 s35, s34, 31
	v_lshl_add_u64 v[158:159], s[14:15], 0, v[158:159]
	v_lshl_add_u64 v[158:159], s[34:35], 1, v[158:159]
	s_lshl_b32 s30, s71, 2
	s_ashr_i32 s31, s30, 31
	s_waitcnt vmcnt(0)
	v_fmamk_f32 v0, v0, 0x3a800000, v233
	s_nop 0
	v_rsq_f32_e32 v0, v0
	s_nop 0
	v_mov_b32_e32 v156, v0
	v_pk_mul_f32 v[128:129], v[128:129], v[156:157] op_sel_hi:[1,0]
	v_pk_mul_f32 v[126:127], v[126:127], v[156:157] op_sel_hi:[1,0]
	v_pk_mul_f32 v[160:161], v[124:125], v[156:157] op_sel_hi:[1,0]
	v_pk_mul_f32 v[124:125], v[122:123], v[156:157] op_sel_hi:[1,0]
	v_mul_f32_e32 v122, v127, v127
	v_mul_f32_e32 v123, v129, v129
	v_fmac_f32_e32 v122, v126, v126
	v_fmac_f32_e32 v123, v128, v128
	v_add_f32_e32 v122, v122, v123
	v_mul_f32_e32 v123, v125, v125
	v_fmac_f32_e32 v123, v124, v124
	v_add_f32_e32 v122, v123, v122
	v_mul_f32_e32 v123, v161, v161
	v_fmac_f32_e32 v123, v160, v160
	v_lshlrev_b32_e32 v0, 1, v138
	v_add_f32_e32 v155, v123, v122
	v_cvt_pk_bf16_f32 v122, v126, v127
	v_cvt_pk_bf16_f32 v123, v128, v129
	v_pk_mul_f32 v[120:121], v[120:121], v[156:157] op_sel_hi:[1,0]
	v_pk_mul_f32 v[118:119], v[118:119], v[156:157] op_sel_hi:[1,0]
	v_lshl_add_u64 v[158:159], v[158:159], 0, v[0:1]
	v_cvt_pk_bf16_f32 v124, v124, v125
	v_cvt_pk_bf16_f32 v125, v160, v161
	global_store_dwordx4 v[158:159], v[122:125], off offset:0 sc1
	s_nop 1
	v_pk_mul_f32 v[122:123], v[116:117], v[156:157] op_sel_hi:[1,0]
	v_pk_mul_f32 v[116:117], v[114:115], v[156:157] op_sel_hi:[1,0]
	v_mul_f32_e32 v114, v119, v119
	v_mul_f32_e32 v115, v121, v121
	v_fmac_f32_e32 v114, v118, v118
	v_fmac_f32_e32 v115, v120, v120
	v_add_f32_e32 v114, v114, v115
	v_mul_f32_e32 v115, v117, v117
	v_fmac_f32_e32 v115, v116, v116
	v_add_f32_e32 v114, v115, v114
	v_mul_f32_e32 v115, v123, v123
	v_fmac_f32_e32 v115, v122, v122
	v_add_f32_e32 v114, v115, v114
	v_cvt_pk_bf16_f32 v115, v120, v121
	v_add_f32_e32 v124, v155, v114
	v_cvt_pk_bf16_f32 v114, v118, v119
	v_cvt_pk_bf16_f32 v116, v116, v117
	v_cvt_pk_bf16_f32 v117, v122, v123
	global_store_dwordx4 v[158:159], v[114:117], off offset:0x100 sc1
	s_nop 1
	v_and_b32_e32 v115, 64, v238
	v_xor_b32_e32 v114, 16, v238
	v_add_u32_e32 v115, 64, v115
	v_cmp_lt_i32_e32 vcc, v114, v115
	v_xor_b32_e32 v117, 32, v238
	s_nop 0
	v_cndmask_b32_e32 v114, v238, v114, vcc
	v_lshlrev_b32_e32 v116, 2, v114
	ds_bpermute_b32 v114, v116, v124
	v_cmp_lt_i32_e32 vcc, v117, v115
	s_waitcnt lgkmcnt(0)
	v_add_f32_e32 v114, v124, v114
	v_cndmask_b32_e32 v115, v238, v117, vcc
	v_lshlrev_b32_e32 v117, 2, v115
	ds_bpermute_b32 v115, v117, v114
	s_and_saveexec_b64 s[36:37], s[8:9]
	s_cbranch_execz .LBB0_680
	v_lshlrev_b64 v[118:119], 6, v[144:145]
	v_lshl_add_u64 v[118:119], s[18:19], 0, v[118:119]
	v_lshl_add_u64 v[118:119], s[30:31], 2, v[118:119]
	s_lshl_b32 s76, s59, 2
	v_lshl_add_u64 v[118:119], v[118:119], 0, s[76:77]
	s_waitcnt lgkmcnt(0)
	v_add_f32_e32 v114, v114, v115
	global_store_dword v[118:119], v114, off

.LBB0_864:
	v_lshl_add_u32 v142, s72, 8, v151
	v_ashrrev_i32_e32 v143, 31, v142
	v_lshl_add_u64 v[160:161], v[142:143], 2, s[10:11]
	global_load_dword v162, v[160:161], off
	global_load_dword v163, v[160:161], off offset:64
	global_load_dword v159, v[160:161], off offset:128
	global_load_dword v158, v[160:161], off offset:192
	global_load_dword v157, v[160:161], off offset:512
	global_load_dword v156, v[160:161], off offset:576
	global_load_dword v155, v[160:161], off offset:640
	global_load_dword v154, v[160:161], off offset:704
	s_lshl_b32 s30, s71, 8
	v_or_b32_e32 v148, 16, v142
	v_or_b32_e32 v146, 32, v142
	v_or_b32_e32 v144, 48, v142
	s_ashr_i32 s31, s30, 31
	v_lshlrev_b64 v[142:143], 13, v[142:143]
	v_ashrrev_i32_e32 v149, 31, v148
	v_lshl_add_u64 v[142:143], s[18:19], 0, v[142:143]
	s_lshl_b64 s[30:31], s[30:31], 1
	v_lshl_add_u64 v[142:143], v[142:143], 0, s[30:31]
	v_ashrrev_i32_e32 v147, 31, v146
	v_lshl_add_u64 v[142:143], v[142:143], 0, v[0:1]
	v_ashrrev_i32_e32 v145, 31, v144
	s_waitcnt vmcnt(0)
	v_fmamk_f32 v160, v162, 0x3a800000, v233
	v_rsq_f32_e32 v160, v160
	s_nop 0
	v_pk_mul_f32 v[120:121], v[120:121], v[160:161] op_sel_hi:[1,0]
	v_pk_mul_f32 v[118:119], v[118:119], v[160:161] op_sel_hi:[1,0]
	v_pk_mul_f32 v[114:115], v[114:115], v[160:161] op_sel_hi:[1,0]
	v_max_f32_e32 v118, 0, v118
	v_max_f32_e32 v119, 0, v119
	v_max_f32_e32 v120, 0, v120
	v_max_f32_e32 v121, 0, v121
	v_max_f32_e32 v114, 0, v114
	v_max_f32_e32 v115, 0, v115
	v_pk_mul_f32 v[118:119], v[118:119], v[118:119]
	v_pk_mul_f32 v[120:121], v[120:121], v[120:121]
	v_pk_mul_f32 v[116:117], v[116:117], v[160:161] op_sel_hi:[1,0]
	v_pk_mul_f32 v[114:115], v[114:115], v[114:115]
	v_cvt_pk_bf16_f32 v118, v118, v119
	v_cvt_pk_bf16_f32 v119, v120, v121
	v_cvt_pk_bf16_f32 v120, v114, v115
	v_max_f32_e32 v114, 0, v116
	v_max_f32_e32 v115, 0, v117
	v_pk_mul_f32 v[114:115], v[114:115], v[114:115]
	v_pk_mul_f32 v[128:129], v[128:129], v[160:161] op_sel_hi:[1,0]
	v_cvt_pk_bf16_f32 v121, v114, v115
	v_fmamk_f32 v114, v163, 0x3a800000, v233
	v_pk_mul_f32 v[126:127], v[126:127], v[160:161] op_sel_hi:[1,0]
	v_rsq_f32_e32 v114, v114
	v_pk_mul_f32 v[122:123], v[122:123], v[160:161] op_sel_hi:[1,0]
	v_max_f32_e32 v126, 0, v126
	v_max_f32_e32 v127, 0, v127
	v_pk_mul_f32 v[104:105], v[104:105], v[114:115] op_sel_hi:[1,0]
	v_pk_mul_f32 v[102:103], v[102:103], v[114:115] op_sel_hi:[1,0]
	v_pk_mul_f32 v[98:99], v[98:99], v[114:115] op_sel_hi:[1,0]
	v_max_f32_e32 v102, 0, v102
	v_max_f32_e32 v103, 0, v103
	v_max_f32_e32 v104, 0, v104
	v_max_f32_e32 v105, 0, v105
	v_max_f32_e32 v98, 0, v98
	v_max_f32_e32 v99, 0, v99
	v_pk_mul_f32 v[102:103], v[102:103], v[102:103]
	v_pk_mul_f32 v[104:105], v[104:105], v[104:105]
	v_pk_mul_f32 v[100:101], v[100:101], v[114:115] op_sel_hi:[1,0]
	v_pk_mul_f32 v[98:99], v[98:99], v[98:99]
	v_cvt_pk_bf16_f32 v102, v102, v103
	v_cvt_pk_bf16_f32 v103, v104, v105
	v_cvt_pk_bf16_f32 v104, v98, v99
	v_max_f32_e32 v98, 0, v100
	v_max_f32_e32 v99, 0, v101
	v_pk_mul_f32 v[98:99], v[98:99], v[98:99]
	v_max_f32_e32 v128, 0, v128
	v_cvt_pk_bf16_f32 v105, v98, v99
	v_fmamk_f32 v98, v159, 0x3a800000, v233
	v_max_f32_e32 v129, 0, v129
	v_rsq_f32_e32 v98, v98
	v_max_f32_e32 v122, 0, v122
	v_max_f32_e32 v123, 0, v123
	v_pk_mul_f32 v[126:127], v[126:127], v[126:127]
	v_pk_mul_f32 v[88:89], v[88:89], v[98:99] op_sel_hi:[1,0]
	v_pk_mul_f32 v[86:87], v[86:87], v[98:99] op_sel_hi:[1,0]
	v_pk_mul_f32 v[82:83], v[82:83], v[98:99] op_sel_hi:[1,0]
	v_max_f32_e32 v86, 0, v86
	v_max_f32_e32 v87, 0, v87
	v_max_f32_e32 v88, 0, v88
	v_max_f32_e32 v89, 0, v89
	v_max_f32_e32 v82, 0, v82
	v_max_f32_e32 v83, 0, v83
	v_pk_mul_f32 v[86:87], v[86:87], v[86:87]
	v_pk_mul_f32 v[88:89], v[88:89], v[88:89]
	v_pk_mul_f32 v[84:85], v[84:85], v[98:99] op_sel_hi:[1,0]
	v_pk_mul_f32 v[82:83], v[82:83], v[82:83]
	v_cvt_pk_bf16_f32 v86, v86, v87
	v_cvt_pk_bf16_f32 v87, v88, v89
	v_cvt_pk_bf16_f32 v88, v82, v83
	v_max_f32_e32 v82, 0, v84
	v_max_f32_e32 v83, 0, v85
	v_pk_mul_f32 v[82:83], v[82:83], v[82:83]
	v_pk_mul_f32 v[128:129], v[128:129], v[128:129]
	v_cvt_pk_bf16_f32 v89, v82, v83
	v_fmamk_f32 v82, v158, 0x3a800000, v233
	v_pk_mul_f32 v[124:125], v[124:125], v[160:161] op_sel_hi:[1,0]
	v_rsq_f32_e32 v82, v82
	v_pk_mul_f32 v[122:123], v[122:123], v[122:123]
	v_pk_mul_f32 v[112:113], v[112:113], v[114:115] op_sel_hi:[1,0]
	v_pk_mul_f32 v[110:111], v[110:111], v[114:115] op_sel_hi:[1,0]
	v_pk_mul_f32 v[72:73], v[72:73], v[82:83] op_sel_hi:[1,0]
	v_pk_mul_f32 v[70:71], v[70:71], v[82:83] op_sel_hi:[1,0]
	v_pk_mul_f32 v[66:67], v[66:67], v[82:83] op_sel_hi:[1,0]
	v_max_f32_e32 v70, 0, v70
	v_max_f32_e32 v71, 0, v71
	v_max_f32_e32 v72, 0, v72
	v_max_f32_e32 v73, 0, v73
	v_max_f32_e32 v66, 0, v66
	v_max_f32_e32 v67, 0, v67
	v_pk_mul_f32 v[70:71], v[70:71], v[70:71]
	v_pk_mul_f32 v[72:73], v[72:73], v[72:73]
	v_pk_mul_f32 v[68:69], v[68:69], v[82:83] op_sel_hi:[1,0]
	v_pk_mul_f32 v[66:67], v[66:67], v[66:67]
	v_cvt_pk_bf16_f32 v70, v70, v71
	v_cvt_pk_bf16_f32 v71, v72, v73
	v_cvt_pk_bf16_f32 v72, v66, v67
	v_max_f32_e32 v66, 0, v68
	v_max_f32_e32 v67, 0, v69
	v_pk_mul_f32 v[66:67], v[66:67], v[66:67]
	v_pk_mul_f32 v[106:107], v[106:107], v[114:115] op_sel_hi:[1,0]
	v_cvt_pk_bf16_f32 v73, v66, v67
	v_fmamk_f32 v66, v157, 0x3a800000, v233
	v_cvt_pk_bf16_f32 v126, v126, v127
	v_rsq_f32_e32 v66, v66
	v_cvt_pk_bf16_f32 v127, v128, v129
	v_cvt_pk_bf16_f32 v128, v122, v123
	v_max_f32_e32 v122, 0, v124
	v_pk_mul_f32 v[56:57], v[56:57], v[66:67] op_sel_hi:[1,0]
	v_pk_mul_f32 v[54:55], v[54:55], v[66:67] op_sel_hi:[1,0]
	v_pk_mul_f32 v[50:51], v[50:51], v[66:67] op_sel_hi:[1,0]
	v_max_f32_e32 v54, 0, v54
	v_max_f32_e32 v55, 0, v55
	v_max_f32_e32 v56, 0, v56
	v_max_f32_e32 v57, 0, v57
	v_max_f32_e32 v50, 0, v50
	v_max_f32_e32 v51, 0, v51
	v_pk_mul_f32 v[54:55], v[54:55], v[54:55]
	v_pk_mul_f32 v[56:57], v[56:57], v[56:57]
	v_pk_mul_f32 v[52:53], v[52:53], v[66:67] op_sel_hi:[1,0]
	v_pk_mul_f32 v[50:51], v[50:51], v[50:51]
	v_cvt_pk_bf16_f32 v54, v54, v55
	v_cvt_pk_bf16_f32 v55, v56, v57
	v_cvt_pk_bf16_f32 v56, v50, v51
	v_max_f32_e32 v50, 0, v52
	v_max_f32_e32 v51, 0, v53
	v_pk_mul_f32 v[50:51], v[50:51], v[50:51]
	v_max_f32_e32 v123, 0, v125
	v_cvt_pk_bf16_f32 v57, v50, v51
	v_fmamk_f32 v50, v156, 0x3a800000, v233
	v_max_f32_e32 v110, 0, v110
	v_rsq_f32_e32 v50, v50
	v_max_f32_e32 v111, 0, v111
	v_max_f32_e32 v112, 0, v112
	v_max_f32_e32 v113, 0, v113
	v_pk_mul_f32 v[40:41], v[40:41], v[50:51] op_sel_hi:[1,0]
	v_pk_mul_f32 v[38:39], v[38:39], v[50:51] op_sel_hi:[1,0]
	v_pk_mul_f32 v[34:35], v[34:35], v[50:51] op_sel_hi:[1,0]
	v_max_f32_e32 v38, 0, v38
	v_max_f32_e32 v39, 0, v39
	v_max_f32_e32 v40, 0, v40
	v_max_f32_e32 v41, 0, v41
	v_max_f32_e32 v34, 0, v34
	v_max_f32_e32 v35, 0, v35
	v_pk_mul_f32 v[38:39], v[38:39], v[38:39]
	v_pk_mul_f32 v[40:41], v[40:41], v[40:41]
	v_pk_mul_f32 v[36:37], v[36:37], v[50:51] op_sel_hi:[1,0]
	v_pk_mul_f32 v[34:35], v[34:35], v[34:35]
	v_cvt_pk_bf16_f32 v38, v38, v39
	v_cvt_pk_bf16_f32 v39, v40, v41
	v_cvt_pk_bf16_f32 v40, v34, v35
	v_max_f32_e32 v34, 0, v36
	v_max_f32_e32 v35, 0, v37
	v_pk_mul_f32 v[34:35], v[34:35], v[34:35]
	v_max_f32_e32 v106, 0, v106
	v_cvt_pk_bf16_f32 v41, v34, v35
	v_fmamk_f32 v34, v155, 0x3a800000, v233
	v_max_f32_e32 v107, 0, v107
	v_rsq_f32_e32 v34, v34
	v_pk_mul_f32 v[122:123], v[122:123], v[122:123]
	v_lshlrev_b64 v[116:117], 13, v[148:149]
	v_pk_mul_f32 v[110:111], v[110:111], v[110:111]
	v_pk_mul_f32 v[24:25], v[24:25], v[34:35] op_sel_hi:[1,0]
	v_pk_mul_f32 v[22:23], v[22:23], v[34:35] op_sel_hi:[1,0]
	v_pk_mul_f32 v[18:19], v[18:19], v[34:35] op_sel_hi:[1,0]
	v_max_f32_e32 v22, 0, v22
	v_max_f32_e32 v23, 0, v23
	v_max_f32_e32 v24, 0, v24
	v_max_f32_e32 v25, 0, v25
	v_max_f32_e32 v18, 0, v18
	v_max_f32_e32 v19, 0, v19
	v_pk_mul_f32 v[22:23], v[22:23], v[22:23]
	v_pk_mul_f32 v[24:25], v[24:25], v[24:25]
	v_pk_mul_f32 v[20:21], v[20:21], v[34:35] op_sel_hi:[1,0]
	v_pk_mul_f32 v[18:19], v[18:19], v[18:19]
	v_cvt_pk_bf16_f32 v22, v22, v23
	v_cvt_pk_bf16_f32 v23, v24, v25
	v_cvt_pk_bf16_f32 v24, v18, v19
	v_max_f32_e32 v18, 0, v20
	v_max_f32_e32 v19, 0, v21
	v_pk_mul_f32 v[112:113], v[112:113], v[112:113]
	v_pk_mul_f32 v[108:109], v[108:109], v[114:115] op_sel_hi:[1,0]
	v_pk_mul_f32 v[106:107], v[106:107], v[106:107]
	v_pk_mul_f32 v[96:97], v[96:97], v[98:99] op_sel_hi:[1,0]
	v_pk_mul_f32 v[94:95], v[94:95], v[98:99] op_sel_hi:[1,0]
	v_pk_mul_f32 v[90:91], v[90:91], v[98:99] op_sel_hi:[1,0]
	v_pk_mul_f32 v[18:19], v[18:19], v[18:19]
	v_cvt_pk_bf16_f32 v129, v122, v123
	global_store_dwordx4 v[142:143], v[126:129], off offset:0 sc1
	s_nop 1
	v_lshl_add_u64 v[116:117], s[18:19], 0, v[116:117]
	v_cvt_pk_bf16_f32 v110, v110, v111
	v_cvt_pk_bf16_f32 v111, v112, v113
	v_cvt_pk_bf16_f32 v112, v106, v107
	v_max_f32_e32 v106, 0, v108
	v_max_f32_e32 v107, 0, v109
	v_max_f32_e32 v94, 0, v94
	v_max_f32_e32 v95, 0, v95
	v_max_f32_e32 v96, 0, v96
	v_max_f32_e32 v97, 0, v97
	v_max_f32_e32 v90, 0, v90
	v_max_f32_e32 v91, 0, v91
	v_cvt_pk_bf16_f32 v25, v18, v19
	v_fmamk_f32 v18, v154, 0x3a800000, v233
	global_store_dwordx4 v[142:143], v[118:121], off offset:0x100 sc1
	s_nop 1
	v_lshl_add_u64 v[116:117], v[116:117], 0, s[30:31]
	v_pk_mul_f32 v[106:107], v[106:107], v[106:107]
	v_lshlrev_b64 v[100:101], 13, v[146:147]
	v_pk_mul_f32 v[94:95], v[94:95], v[94:95]
	v_pk_mul_f32 v[96:97], v[96:97], v[96:97]
	v_pk_mul_f32 v[92:93], v[92:93], v[98:99] op_sel_hi:[1,0]
	v_pk_mul_f32 v[90:91], v[90:91], v[90:91]
	v_pk_mul_f32 v[80:81], v[80:81], v[82:83] op_sel_hi:[1,0]
	v_pk_mul_f32 v[78:79], v[78:79], v[82:83] op_sel_hi:[1,0]
	v_pk_mul_f32 v[74:75], v[74:75], v[82:83] op_sel_hi:[1,0]
	v_cmp_gt_f32_e32 vcc, s82, v18
	v_mul_f32_e32 v19, 0x4b800000, v18
	v_lshl_add_u64 v[116:117], v[116:117], 0, v[0:1]
	v_cvt_pk_bf16_f32 v113, v106, v107
	global_store_dwordx4 v[116:117], v[110:113], off offset:0 sc1
	s_nop 1
	v_lshl_add_u64 v[100:101], s[18:19], 0, v[100:101]
	v_cvt_pk_bf16_f32 v94, v94, v95
	v_cvt_pk_bf16_f32 v95, v96, v97
	v_cvt_pk_bf16_f32 v96, v90, v91
	v_max_f32_e32 v90, 0, v92
	v_max_f32_e32 v91, 0, v93
	v_max_f32_e32 v78, 0, v78
	v_max_f32_e32 v79, 0, v79
	v_max_f32_e32 v80, 0, v80
	v_max_f32_e32 v81, 0, v81
	v_max_f32_e32 v74, 0, v74
	v_max_f32_e32 v75, 0, v75
	v_cndmask_b32_e32 v18, v18, v19, vcc
	global_store_dwordx4 v[116:117], v[102:105], off offset:0x100 sc1
	s_nop 1
	v_lshl_add_u64 v[100:101], v[100:101], 0, s[30:31]
	v_pk_mul_f32 v[90:91], v[90:91], v[90:91]
	v_lshlrev_b64 v[84:85], 13, v[144:145]
	v_pk_mul_f32 v[78:79], v[78:79], v[78:79]
	v_pk_mul_f32 v[80:81], v[80:81], v[80:81]
	v_pk_mul_f32 v[76:77], v[76:77], v[82:83] op_sel_hi:[1,0]
	v_pk_mul_f32 v[74:75], v[74:75], v[74:75]
	v_pk_mul_f32 v[64:65], v[64:65], v[66:67] op_sel_hi:[1,0]
	v_pk_mul_f32 v[62:63], v[62:63], v[66:67] op_sel_hi:[1,0]
	v_pk_mul_f32 v[58:59], v[58:59], v[66:67] op_sel_hi:[1,0]
	v_rsq_f32_e32 v18, v18
	v_lshl_add_u64 v[100:101], v[100:101], 0, v[0:1]
	v_cvt_pk_bf16_f32 v97, v90, v91
	global_store_dwordx4 v[100:101], v[94:97], off offset:0 sc1
	s_nop 1
	v_lshl_add_u64 v[84:85], s[18:19], 0, v[84:85]
	v_cvt_pk_bf16_f32 v78, v78, v79
	v_cvt_pk_bf16_f32 v79, v80, v81
	v_cvt_pk_bf16_f32 v80, v74, v75
	v_max_f32_e32 v74, 0, v76
	v_max_f32_e32 v75, 0, v77
	v_max_f32_e32 v62, 0, v62
	v_max_f32_e32 v63, 0, v63
	v_max_f32_e32 v64, 0, v64
	v_max_f32_e32 v65, 0, v65
	v_max_f32_e32 v58, 0, v58
	v_max_f32_e32 v59, 0, v59
	global_store_dwordx4 v[100:101], v[86:89], off offset:0x100 sc1
	s_nop 1
	v_lshl_add_u64 v[84:85], v[84:85], 0, s[30:31]
	v_pk_mul_f32 v[74:75], v[74:75], v[74:75]
	v_pk_mul_f32 v[62:63], v[62:63], v[62:63]
	v_pk_mul_f32 v[64:65], v[64:65], v[64:65]
	v_pk_mul_f32 v[60:61], v[60:61], v[66:67] op_sel_hi:[1,0]
	v_pk_mul_f32 v[58:59], v[58:59], v[58:59]
	v_pk_mul_f32 v[48:49], v[48:49], v[50:51] op_sel_hi:[1,0]
	v_pk_mul_f32 v[46:47], v[46:47], v[50:51] op_sel_hi:[1,0]
	v_pk_mul_f32 v[42:43], v[42:43], v[50:51] op_sel_hi:[1,0]
	v_lshl_add_u64 v[84:85], v[84:85], 0, v[0:1]
	v_cvt_pk_bf16_f32 v81, v74, v75
	global_store_dwordx4 v[84:85], v[78:81], off offset:0 sc1
	s_nop 1
	v_cvt_pk_bf16_f32 v62, v62, v63
	v_cvt_pk_bf16_f32 v63, v64, v65
	v_cvt_pk_bf16_f32 v64, v58, v59
	v_max_f32_e32 v58, 0, v60
	v_max_f32_e32 v59, 0, v61
	v_max_f32_e32 v46, 0, v46
	v_max_f32_e32 v47, 0, v47
	v_max_f32_e32 v48, 0, v48
	v_max_f32_e32 v49, 0, v49
	v_max_f32_e32 v42, 0, v42
	v_max_f32_e32 v43, 0, v43
	global_store_dwordx4 v[84:85], v[70:73], off offset:0x100 sc1
	s_nop 1
	s_mov_b64 s[30:31], 0x100000
	v_pk_mul_f32 v[58:59], v[58:59], v[58:59]
	v_pk_mul_f32 v[46:47], v[46:47], v[46:47]
	v_pk_mul_f32 v[48:49], v[48:49], v[48:49]
	v_pk_mul_f32 v[44:45], v[44:45], v[50:51] op_sel_hi:[1,0]
	v_pk_mul_f32 v[42:43], v[42:43], v[42:43]
	v_pk_mul_f32 v[32:33], v[32:33], v[34:35] op_sel_hi:[1,0]
	v_pk_mul_f32 v[30:31], v[30:31], v[34:35] op_sel_hi:[1,0]
	v_pk_mul_f32 v[26:27], v[26:27], v[34:35] op_sel_hi:[1,0]
	v_mul_f32_e32 v19, 0x45800000, v18
	v_lshl_add_u64 v[68:69], v[142:143], 0, s[30:31]
	v_cvt_pk_bf16_f32 v65, v58, v59
	global_store_dwordx4 v[68:69], v[62:65], off offset:0 sc1
	s_nop 1
	v_cvt_pk_bf16_f32 v46, v46, v47
	v_cvt_pk_bf16_f32 v47, v48, v49
	v_cvt_pk_bf16_f32 v48, v42, v43
	v_max_f32_e32 v42, 0, v44
	v_max_f32_e32 v43, 0, v45
	v_max_f32_e32 v30, 0, v30
	v_max_f32_e32 v31, 0, v31
	v_max_f32_e32 v32, 0, v32
	v_max_f32_e32 v33, 0, v33
	v_max_f32_e32 v26, 0, v26
	v_max_f32_e32 v27, 0, v27
	v_cndmask_b32_e32 v18, v18, v19, vcc
	global_store_dwordx4 v[68:69], v[54:57], off offset:0x100 sc1
	s_nop 1
	s_mov_b64 s[30:31], 0x120000
	v_pk_mul_f32 v[42:43], v[42:43], v[42:43]
	v_pk_mul_f32 v[30:31], v[30:31], v[30:31]
	v_pk_mul_f32 v[32:33], v[32:33], v[32:33]
	v_pk_mul_f32 v[28:29], v[28:29], v[34:35] op_sel_hi:[1,0]
	v_pk_mul_f32 v[26:27], v[26:27], v[26:27]
	v_pk_mul_f32 v[16:17], v[16:17], v[18:19] op_sel_hi:[1,0]
	v_pk_mul_f32 v[14:15], v[14:15], v[18:19] op_sel_hi:[1,0]
	v_pk_mul_f32 v[10:11], v[10:11], v[18:19] op_sel_hi:[1,0]
	v_lshl_add_u64 v[52:53], v[142:143], 0, s[30:31]
	v_cvt_pk_bf16_f32 v49, v42, v43
	global_store_dwordx4 v[52:53], v[46:49], off offset:0 sc1
	s_nop 1
	v_cvt_pk_bf16_f32 v30, v30, v31
	v_cvt_pk_bf16_f32 v31, v32, v33
	v_cvt_pk_bf16_f32 v32, v26, v27
	v_max_f32_e32 v26, 0, v28
	v_max_f32_e32 v27, 0, v29
	v_max_f32_e32 v14, 0, v14
	v_max_f32_e32 v15, 0, v15
	v_max_f32_e32 v16, 0, v16
	v_max_f32_e32 v17, 0, v17
	v_max_f32_e32 v10, 0, v10
	v_max_f32_e32 v11, 0, v11
	v_pk_mul_f32 v[8:9], v[8:9], v[18:19] op_sel_hi:[1,0]
	v_pk_mul_f32 v[6:7], v[6:7], v[18:19] op_sel_hi:[1,0]
	v_pk_mul_f32 v[2:3], v[2:3], v[18:19] op_sel_hi:[1,0]
	global_store_dwordx4 v[52:53], v[38:41], off offset:0x100 sc1
	s_nop 1
	s_mov_b64 s[30:31], 0x140000
	v_pk_mul_f32 v[26:27], v[26:27], v[26:27]
	v_pk_mul_f32 v[14:15], v[14:15], v[14:15]
	v_pk_mul_f32 v[16:17], v[16:17], v[16:17]
	v_pk_mul_f32 v[12:13], v[12:13], v[18:19] op_sel_hi:[1,0]
	v_pk_mul_f32 v[10:11], v[10:11], v[10:11]
	v_max_f32_e32 v6, 0, v6
	v_max_f32_e32 v7, 0, v7
	v_max_f32_e32 v8, 0, v8
	v_max_f32_e32 v9, 0, v9
	v_max_f32_e32 v2, 0, v2
	v_max_f32_e32 v3, 0, v3
	v_lshl_add_u64 v[36:37], v[142:143], 0, s[30:31]
	v_cvt_pk_bf16_f32 v33, v26, v27
	global_store_dwordx4 v[36:37], v[30:33], off offset:0 sc1
	s_nop 1
	v_cvt_pk_bf16_f32 v14, v14, v15
	v_cvt_pk_bf16_f32 v15, v16, v17
	v_cvt_pk_bf16_f32 v16, v10, v11
	v_max_f32_e32 v10, 0, v12
	v_max_f32_e32 v11, 0, v13
	v_pk_mul_f32 v[6:7], v[6:7], v[6:7]
	v_pk_mul_f32 v[8:9], v[8:9], v[8:9]
	v_pk_mul_f32 v[4:5], v[4:5], v[18:19] op_sel_hi:[1,0]
	v_pk_mul_f32 v[2:3], v[2:3], v[2:3]
	global_store_dwordx4 v[36:37], v[22:25], off offset:0x100 sc1
	s_nop 1
	s_mov_b64 s[30:31], 0x160000
	v_pk_mul_f32 v[10:11], v[10:11], v[10:11]
	v_cvt_pk_bf16_f32 v6, v6, v7
	v_cvt_pk_bf16_f32 v7, v8, v9
	v_cvt_pk_bf16_f32 v8, v2, v3
	v_max_f32_e32 v2, 0, v4
	v_max_f32_e32 v3, 0, v5
	v_lshl_add_u64 v[20:21], v[142:143], 0, s[30:31]
	v_cvt_pk_bf16_f32 v17, v10, v11
	global_store_dwordx4 v[20:21], v[14:17], off offset:0 sc1
	s_nop 1
	v_pk_mul_f32 v[2:3], v[2:3], v[2:3]
	s_mov_b64 s[30:31], -1
	v_cvt_pk_bf16_f32 v9, v2, v3
	global_store_dwordx4 v[20:21], v[6:9], off offset:0x100 sc1
	s_nop 1
	s_andn2_b64 vcc, exec, s[8:9]
	s_cbranch_vccnz .LBB0_853
	s_andn2_b64 vcc, exec, s[16:17]
	s_cbranch_vccnz .LBB0_852
	s_barrier
	s_branch .LBB0_852
